# GEMM K-loops: dropped the redundant second s_waitcnt lgkmcnt(0) at each MFMA segment head (plus mid-segment setprio flip removal)
# baseline (speedup 1.0000x reference)
; #define PG8_STAGE(bufoff, gbase, voff) do { _Pragma("unroll") for (int _i = 0; _i < 2; ++_i) \
;         __builtin_amdgcn_global_load_lds((const unsigned*)((const char*)(gbase) + (voff)[_i]), (LAS unsigned*)(lds + (bufoff) + ldsw + _i * 8192), 16, 0, 0); } while (0)
; #define PG8_LDA(dst, b, h) do { _Pragma("unroll") for (int m = 0; m < 4; ++m) _Pragma("unroll") for (int k = 0; k < 2; ++k) dst[m][k] = *(const LAS bf16x8*)(lds + PG8_SA(b, h) + aoff + m * 2048 + k * 1024); } while (0)
; #define PG8_LDB(dst, b, h) do { _Pragma("unroll") for (int n = 0; n < 2; ++n) _Pragma("unroll") for (int k = 0; k < 2; ++k) dst[n][k] = *(const LAS bf16x8*)(lds + PG8_SB(b, h) + boff + n * 2048 + k * 1024); } while (0)
; #define PG8_MMA(ai, bj, At, Bt) do { __builtin_amdgcn_s_setprio(1); _Pragma("unroll") for (int m = 0; m < 4; ++m) _Pragma("unroll") for (int n = 0; n < 2; ++n) _Pragma("unroll") for (int k = 0; k < 2; ++k) \
;         acc[ai][bj][m][n] = __builtin_amdgcn_mfma_f32_16x16x32_bf16(Bt[n][k], At[m][k], acc[ai][bj][m][n], 0, 0, 0); __builtin_amdgcn_s_setprio(0); } while (0)
; #define PG8_WAIT_V(n) asm volatile("s_waitcnt vmcnt(" #n ")" ::: "memory")
; #define PG8_WAIT_L(n) asm volatile("s_waitcnt lgkmcnt(" #n ")" ::: "memory")
; template <class Epi, class Sched, bool ALIGN_EPI>
; __device__ __forceinline__ void gemm_phase(LAS unsigned char* lds, const Gemm g, const Sched& S, const Epi& E, const int tid) {
;     ...
;         const bool has_next = S.next(ui + 1, nxt);
;         const char* nA = has_next ? (const char*)g.A + (size_t)nxt.pm * tstepA : cA; const char* nB = has_next ? (const char*)g.Bt + (size_t)nxt.pn * tstepB : cB;
;         for (int t = 0; t < nt; t += 2) {
;             const bool last = (t == nt - 2);
;             const char* a1 = cA + (size_t)(t + 1) * kstep;
;             const char* a2 = last ? nA : cA + (size_t)(t + 2) * kstep; const char* b2 = last ? nB : cB + (size_t)(t + 2) * kstep;
;             const char* a3 = a2 + kstep; const char* b3 = b2 + kstep;
;             PG8_LDB(B0, 0, 0); PG8_LDB(B1, 0, 1); PG8_SCHED; PG8_LDA(At, 0, 0); PG8_STAGE(PG8_SA(1, 1), a1 + hstepA, voffA);
;             PG8_WAIT_V(8); PG8_WAIT_L(0); PG8_BAR; PG8_MMA(0, 0, At, B0); PG8_MMA(0, 1, At, B1); PG8_BAR; PG8_SCHED;
;             PG8_LDA(At, 0, 1); PG8_STAGE(PG8_SB(0, 0), b2, voffB); PG8_STAGE(PG8_SB(0, 1), b2 + hstepB, voffB); PG8_STAGE(PG8_SA(0, 0), a2, voffA);
.LBB0_71:
	s_add_u32 s52, s50, 0xfffc0080
	s_addc_u32 s53, s51, -1
	s_add_i32 s74, 0, 0x10000
	s_cmp_eq_u32 s73, 12
	s_cselect_b32 s55, s41, s53
	s_cselect_b32 s54, s47, s52
	s_cselect_b32 s53, s39, s72
	s_cselect_b32 s52, s49, s71
	s_add_i32 s76, 0, 0x14000
	v_add_u32_e32 v84, s74, v190
	v_add_u32_e32 v136, s76, v190
	ds_read_b128 v[64:67], v84
	ds_read_b128 v[68:71], v84 offset:1024
	ds_read_b128 v[80:83], v84 offset:2048
	ds_read_b128 v[84:87], v84 offset:3072
	ds_read_b128 v[88:91], v136
	ds_read_b128 v[92:95], v136 offset:1024
	ds_read_b128 v[132:135], v136 offset:2048
	ds_read_b128 v[136:139], v136 offset:3072
	v_lshl_add_u64 v[220:221], s[50:51], 0, v[178:179]
	s_add_i32 m0, s61, 0xc000
	ds_read_b128 v[160:163], v193
	ds_read_b128 v[182:185], v193 offset:1024
	ds_read_b128 v[186:189], v193 offset:2048
	ds_read_b128 v[194:197], v193 offset:3072
	ds_read_b128 v[198:201], v193 offset:4096
	ds_read_b128 v[202:205], v193 offset:5120
	ds_read_b128 v[210:213], v193 offset:6144
	ds_read_b128 v[216:219], v193 offset:7168
	global_load_lds_dwordx4 v[220:221], off
	v_lshl_add_u64 v[220:221], s[50:51], 0, v[180:181]
	s_add_i32 m0, s61, 0xe000
	s_nop 0
	global_load_lds_dwordx4 v[220:221], off
	s_waitcnt vmcnt(8)
	s_waitcnt lgkmcnt(0)
	s_barrier
	s_setprio 1
	v_mfma_f32_16x16x32_bf16 v[148:151], v[64:67], v[160:163], v[148:151]
	v_mfma_f32_16x16x32_bf16 v[140:143], v[80:83], v[160:163], v[140:143]
	v_mfma_f32_16x16x32_bf16 v[124:127], v[64:67], v[186:189], v[124:127]
	v_mfma_f32_16x16x32_bf16 v[116:119], v[80:83], v[186:189], v[116:119]
	v_mfma_f32_16x16x32_bf16 v[108:111], v[64:67], v[198:201], v[108:111]
	v_mfma_f32_16x16x32_bf16 v[100:103], v[80:83], v[198:201], v[100:103]
	v_mfma_f32_16x16x32_bf16 v[104:107], v[64:67], v[210:213], v[104:107]
	v_mfma_f32_16x16x32_bf16 v[76:79], v[80:83], v[210:213], v[76:79]
	v_mfma_f32_16x16x32_bf16 v[148:151], v[68:71], v[182:185], v[148:151]
	v_mfma_f32_16x16x32_bf16 v[140:143], v[84:87], v[182:185], v[140:143]
	v_mfma_f32_16x16x32_bf16 v[124:127], v[68:71], v[194:197], v[124:127]
	v_mfma_f32_16x16x32_bf16 v[116:119], v[84:87], v[194:197], v[116:119]
	v_mfma_f32_16x16x32_bf16 v[108:111], v[68:71], v[202:205], v[108:111]
	v_mfma_f32_16x16x32_bf16 v[100:103], v[84:87], v[202:205], v[100:103]
	v_mfma_f32_16x16x32_bf16 v[104:107], v[68:71], v[216:219], v[104:107]
	v_mfma_f32_16x16x32_bf16 v[76:79], v[84:87], v[216:219], v[76:79]
	v_mfma_f32_16x16x32_bf16 v[156:159], v[88:91], v[160:163], v[156:159]
	v_mfma_f32_16x16x32_bf16 v[152:155], v[132:135], v[160:163], v[152:155]
	v_mfma_f32_16x16x32_bf16 v[144:147], v[88:91], v[186:189], v[144:147]
	v_mfma_f32_16x16x32_bf16 v[128:131], v[132:135], v[186:189], v[128:131]
	v_mfma_f32_16x16x32_bf16 v[120:123], v[88:91], v[198:201], v[120:123]
	v_mfma_f32_16x16x32_bf16 v[112:115], v[132:135], v[198:201], v[112:115]
	v_mfma_f32_16x16x32_bf16 v[96:99], v[88:91], v[210:213], v[96:99]
	v_mfma_f32_16x16x32_bf16 v[72:75], v[132:135], v[210:213], v[72:75]
	v_mfma_f32_16x16x32_bf16 v[156:159], v[92:95], v[182:185], v[156:159]
	v_mfma_f32_16x16x32_bf16 v[152:155], v[136:139], v[182:185], v[152:155]
	v_mfma_f32_16x16x32_bf16 v[144:147], v[92:95], v[194:197], v[144:147]
	v_mfma_f32_16x16x32_bf16 v[128:131], v[136:139], v[194:197], v[128:131]
	v_mfma_f32_16x16x32_bf16 v[120:123], v[92:95], v[202:205], v[120:123]
	v_mfma_f32_16x16x32_bf16 v[112:115], v[136:139], v[202:205], v[112:115]
	v_mfma_f32_16x16x32_bf16 v[96:99], v[92:95], v[216:219], v[96:99]
	v_mfma_f32_16x16x32_bf16 v[72:75], v[136:139], v[216:219], v[72:75]
	s_setprio 0
	s_barrier
	s_add_i32 s74, s74, s60
	v_lshl_add_u64 v[220:221], s[52:53], 0, v[164:165]
	s_mov_b32 m0, s74
	ds_read_b128 v[160:163], v193 offset:16384
	ds_read_b128 v[182:185], v193 offset:17408
	ds_read_b128 v[186:189], v193 offset:18432
	ds_read_b128 v[194:197], v193 offset:19456
	ds_read_b128 v[198:201], v193 offset:20480
	ds_read_b128 v[202:205], v193 offset:21504
	ds_read_b128 v[210:213], v193 offset:22528
	ds_read_b128 v[216:219], v193 offset:23552
	global_load_lds_dwordx4 v[220:221], off
	s_add_i32 m0, s74, 0x2000
	s_add_u32 s74, s52, 0x40000
	v_lshl_add_u64 v[222:223], s[52:53], 0, v[176:177]
	s_addc_u32 s75, s53, 0
	s_add_i32 s76, s76, s60
	global_load_lds_dwordx4 v[222:223], off
	v_lshl_add_u64 v[224:225], s[74:75], 0, v[164:165]
	s_mov_b32 m0, s76
	v_lshl_add_u64 v[226:227], s[54:55], 0, v[174:175]
	global_load_lds_dwordx4 v[224:225], off
	v_lshl_add_u64 v[224:225], s[74:75], 0, v[176:177]
	s_add_i32 m0, s76, 0x2000
	s_nop 0
	global_load_lds_dwordx4 v[224:225], off
	v_lshl_add_u64 v[224:225], s[54:55], 0, v[172:173]
	s_mov_b32 m0, s61
	s_nop 0
	global_load_lds_dwordx4 v[224:225], off
	s_mov_b32 m0, s62
	s_nop 0
	global_load_lds_dwordx4 v[226:227], off
	s_waitcnt vmcnt(8)
	s_waitcnt lgkmcnt(0)
	s_barrier
; #define PG8_STAGE(bufoff, gbase, voff) do { _Pragma("unroll") for (int _i = 0; _i < 2; ++_i) \
;         __builtin_amdgcn_global_load_lds((const unsigned*)((const char*)(gbase) + (voff)[_i]), (LAS unsigned*)(lds + (bufoff) + ldsw + _i * 8192), 16, 0, 0); } while (0)
; #define PG8_LDA(dst, b, h) do { _Pragma("unroll") for (int m = 0; m < 4; ++m) _Pragma("unroll") for (int k = 0; k < 2; ++k) dst[m][k] = *(const LAS bf16x8*)(lds + PG8_SA(b, h) + aoff + m * 2048 + k * 1024); } while (0)
; #define PG8_LDB(dst, b, h) do { _Pragma("unroll") for (int n = 0; n < 2; ++n) _Pragma("unroll") for (int k = 0; k < 2; ++k) dst[n][k] = *(const LAS bf16x8*)(lds + PG8_SB(b, h) + boff + n * 2048 + k * 1024); } while (0)
; #define PG8_MMA(ai, bj, At, Bt) do { __builtin_amdgcn_s_setprio(1); _Pragma("unroll") for (int m = 0; m < 4; ++m) _Pragma("unroll") for (int n = 0; n < 2; ++n) _Pragma("unroll") for (int k = 0; k < 2; ++k) \
;         acc[ai][bj][m][n] = __builtin_amdgcn_mfma_f32_16x16x32_bf16(Bt[n][k], At[m][k], acc[ai][bj][m][n], 0, 0, 0); __builtin_amdgcn_s_setprio(0); } while (0)
; #define PG8_WAIT_V(n) asm volatile("s_waitcnt vmcnt(" #n ")" ::: "memory")
; #define PG8_WAIT_L(n) asm volatile("s_waitcnt lgkmcnt(" #n ")" ::: "memory")
; #define PG8_BAR __builtin_amdgcn_s_barrier()
; #define PG8_SCHED __builtin_amdgcn_sched_barrier(0)
; template <class Epi, class Sched, bool ALIGN_EPI>
; __device__ __forceinline__ void gemm_phase(LAS unsigned char* lds, const Gemm g, const Sched& S, const Epi& E, const int tid) {
;     ...
;             PG8_WAIT_V(8); PG8_WAIT_L(0); PG8_BAR; PG8_MMA(1, 0, At, B0); PG8_MMA(1, 1, At, B1); PG8_BAR; PG8_SCHED;
;             PG8_LDB(B0, 1, 0); PG8_LDB(B1, 1, 1); PG8_SCHED; PG8_LDA(At, 1, 0); PG8_STAGE(PG8_SA(0, 1), a2 + hstepA, voffA);
;             PG8_WAIT_V(8); PG8_WAIT_L(0); PG8_BAR; PG8_MMA(0, 0, At, B0); PG8_MMA(0, 1, At, B1); PG8_BAR; PG8_SCHED;
	s_setprio 1
	v_mfma_f32_16x16x32_bf16 v[52:55], v[64:67], v[160:163], v[52:55]
	v_mfma_f32_16x16x32_bf16 v[44:47], v[80:83], v[160:163], v[44:47]
	v_mfma_f32_16x16x32_bf16 v[36:39], v[64:67], v[186:189], v[36:39]
	v_mfma_f32_16x16x32_bf16 v[28:31], v[80:83], v[186:189], v[28:31]
	v_mfma_f32_16x16x32_bf16 v[24:27], v[64:67], v[198:201], v[24:27]
	v_mfma_f32_16x16x32_bf16 v[12:15], v[80:83], v[198:201], v[12:15]
	v_mfma_f32_16x16x32_bf16 v[16:19], v[64:67], v[210:213], v[16:19]
	v_mfma_f32_16x16x32_bf16 v[4:7], v[80:83], v[210:213], v[4:7]
	v_mfma_f32_16x16x32_bf16 v[52:55], v[68:71], v[182:185], v[52:55]
	v_mfma_f32_16x16x32_bf16 v[44:47], v[84:87], v[182:185], v[44:47]
	v_mfma_f32_16x16x32_bf16 v[36:39], v[68:71], v[194:197], v[36:39]
	v_mfma_f32_16x16x32_bf16 v[28:31], v[84:87], v[194:197], v[28:31]
	v_mfma_f32_16x16x32_bf16 v[24:27], v[68:71], v[202:205], v[24:27]
	v_mfma_f32_16x16x32_bf16 v[12:15], v[84:87], v[202:205], v[12:15]
	v_mfma_f32_16x16x32_bf16 v[16:19], v[68:71], v[216:219], v[16:19]
	v_mfma_f32_16x16x32_bf16 v[4:7], v[84:87], v[216:219], v[4:7]
	v_mfma_f32_16x16x32_bf16 v[60:63], v[88:91], v[160:163], v[60:63]
	v_mfma_f32_16x16x32_bf16 v[56:59], v[132:135], v[160:163], v[56:59]
	v_mfma_f32_16x16x32_bf16 v[48:51], v[88:91], v[186:189], v[48:51]
	v_mfma_f32_16x16x32_bf16 v[40:43], v[132:135], v[186:189], v[40:43]
	v_mfma_f32_16x16x32_bf16 v[32:35], v[88:91], v[198:201], v[32:35]
	v_mfma_f32_16x16x32_bf16 v[20:23], v[132:135], v[198:201], v[20:23]
	v_mfma_f32_16x16x32_bf16 v[8:11], v[88:91], v[210:213], v[8:11]
	v_mfma_f32_16x16x32_bf16 v[0:3], v[132:135], v[210:213], v[0:3]
	v_mfma_f32_16x16x32_bf16 v[60:63], v[92:95], v[182:185], v[60:63]
	v_mfma_f32_16x16x32_bf16 v[56:59], v[136:139], v[182:185], v[56:59]
	v_mfma_f32_16x16x32_bf16 v[48:51], v[92:95], v[194:197], v[48:51]
	v_mfma_f32_16x16x32_bf16 v[40:43], v[136:139], v[194:197], v[40:43]
	v_mfma_f32_16x16x32_bf16 v[32:35], v[92:95], v[202:205], v[32:35]
	v_mfma_f32_16x16x32_bf16 v[20:23], v[136:139], v[202:205], v[20:23]
	v_mfma_f32_16x16x32_bf16 v[8:11], v[92:95], v[216:219], v[8:11]
	v_mfma_f32_16x16x32_bf16 v[0:3], v[136:139], v[216:219], v[0:3]
	s_setprio 0
	s_barrier
	s_add_i32 s74, 0, 0x18000
	s_add_i32 s75, 0, 0x1c000
	v_add_u32_e32 v84, s74, v190
	v_add_u32_e32 v136, s75, v190
	ds_read_b128 v[64:67], v84
	ds_read_b128 v[68:71], v84 offset:1024
	ds_read_b128 v[80:83], v84 offset:2048
	ds_read_b128 v[84:87], v84 offset:3072
	ds_read_b128 v[88:91], v136
	ds_read_b128 v[92:95], v136 offset:1024
	ds_read_b128 v[132:135], v136 offset:2048
	ds_read_b128 v[136:139], v136 offset:3072
	s_add_u32 s54, s54, 0x40000
	s_addc_u32 s55, s55, 0
	s_mov_b32 m0, s63
	v_lshl_add_u64 v[228:229], s[54:55], 0, v[172:173]
	ds_read_b128 v[160:163], v193 offset:32768
	ds_read_b128 v[182:185], v193 offset:33792
	ds_read_b128 v[186:189], v193 offset:34816
	ds_read_b128 v[194:197], v193 offset:35840
	ds_read_b128 v[198:201], v193 offset:36864
	ds_read_b128 v[202:205], v193 offset:37888
	ds_read_b128 v[210:213], v193 offset:38912
	ds_read_b128 v[216:219], v193 offset:39936
	global_load_lds_dwordx4 v[228:229], off
	v_lshl_add_u64 v[228:229], s[54:55], 0, v[174:175]
	s_mov_b32 m0, s64
	s_nop 0
	global_load_lds_dwordx4 v[228:229], off
	s_waitcnt vmcnt(8)
	s_waitcnt lgkmcnt(0)
	s_barrier
	s_setprio 1
	v_mfma_f32_16x16x32_bf16 v[148:151], v[64:67], v[160:163], v[148:151]
	v_mfma_f32_16x16x32_bf16 v[140:143], v[80:83], v[160:163], v[140:143]
	v_mfma_f32_16x16x32_bf16 v[124:127], v[64:67], v[186:189], v[124:127]
	v_mfma_f32_16x16x32_bf16 v[116:119], v[80:83], v[186:189], v[116:119]
	v_mfma_f32_16x16x32_bf16 v[108:111], v[64:67], v[198:201], v[108:111]
	v_mfma_f32_16x16x32_bf16 v[100:103], v[80:83], v[198:201], v[100:103]
	v_mfma_f32_16x16x32_bf16 v[104:107], v[64:67], v[210:213], v[104:107]
	v_mfma_f32_16x16x32_bf16 v[76:79], v[80:83], v[210:213], v[76:79]
	v_mfma_f32_16x16x32_bf16 v[148:151], v[68:71], v[182:185], v[148:151]
	v_mfma_f32_16x16x32_bf16 v[140:143], v[84:87], v[182:185], v[140:143]
	v_mfma_f32_16x16x32_bf16 v[124:127], v[68:71], v[194:197], v[124:127]
	v_mfma_f32_16x16x32_bf16 v[116:119], v[84:87], v[194:197], v[116:119]
	v_mfma_f32_16x16x32_bf16 v[108:111], v[68:71], v[202:205], v[108:111]
	v_mfma_f32_16x16x32_bf16 v[100:103], v[84:87], v[202:205], v[100:103]
	v_mfma_f32_16x16x32_bf16 v[104:107], v[68:71], v[216:219], v[104:107]
	v_mfma_f32_16x16x32_bf16 v[76:79], v[84:87], v[216:219], v[76:79]
	v_mfma_f32_16x16x32_bf16 v[156:159], v[88:91], v[160:163], v[156:159]
	v_mfma_f32_16x16x32_bf16 v[152:155], v[132:135], v[160:163], v[152:155]
	v_mfma_f32_16x16x32_bf16 v[144:147], v[88:91], v[186:189], v[144:147]
	v_mfma_f32_16x16x32_bf16 v[128:131], v[132:135], v[186:189], v[128:131]
	v_mfma_f32_16x16x32_bf16 v[120:123], v[88:91], v[198:201], v[120:123]
	v_mfma_f32_16x16x32_bf16 v[112:115], v[132:135], v[198:201], v[112:115]
	v_mfma_f32_16x16x32_bf16 v[96:99], v[88:91], v[210:213], v[96:99]
	v_mfma_f32_16x16x32_bf16 v[72:75], v[132:135], v[210:213], v[72:75]
	v_mfma_f32_16x16x32_bf16 v[156:159], v[92:95], v[182:185], v[156:159]
	v_mfma_f32_16x16x32_bf16 v[152:155], v[136:139], v[182:185], v[152:155]
	v_mfma_f32_16x16x32_bf16 v[144:147], v[92:95], v[194:197], v[144:147]
	v_mfma_f32_16x16x32_bf16 v[128:131], v[136:139], v[194:197], v[128:131]
	v_mfma_f32_16x16x32_bf16 v[120:123], v[92:95], v[202:205], v[120:123]
	v_mfma_f32_16x16x32_bf16 v[112:115], v[136:139], v[202:205], v[112:115]
	v_mfma_f32_16x16x32_bf16 v[96:99], v[92:95], v[216:219], v[96:99]
	v_mfma_f32_16x16x32_bf16 v[72:75], v[136:139], v[216:219], v[72:75]
	s_setprio 0
	s_barrier
; #define PG8_STAGE(bufoff, gbase, voff) do { _Pragma("unroll") for (int _i = 0; _i < 2; ++_i) \
;         __builtin_amdgcn_global_load_lds((const unsigned*)((const char*)(gbase) + (voff)[_i]), (LAS unsigned*)(lds + (bufoff) + ldsw + _i * 8192), 16, 0, 0); } while (0)
; #define PG8_LDA(dst, b, h) do { _Pragma("unroll") for (int m = 0; m < 4; ++m) _Pragma("unroll") for (int k = 0; k < 2; ++k) dst[m][k] = *(const LAS bf16x8*)(lds + PG8_SA(b, h) + aoff + m * 2048 + k * 1024); } while (0)
; #define PG8_MMA(ai, bj, At, Bt) do { __builtin_amdgcn_s_setprio(1); _Pragma("unroll") for (int m = 0; m < 4; ++m) _Pragma("unroll") for (int n = 0; n < 2; ++n) _Pragma("unroll") for (int k = 0; k < 2; ++k) \
;         acc[ai][bj][m][n] = __builtin_amdgcn_mfma_f32_16x16x32_bf16(Bt[n][k], At[m][k], acc[ai][bj][m][n], 0, 0, 0); __builtin_amdgcn_s_setprio(0); } while (0)
; #define PG8_WAIT_V(n) asm volatile("s_waitcnt vmcnt(" #n ")" ::: "memory")
; #define PG8_WAIT_L(n) asm volatile("s_waitcnt lgkmcnt(" #n ")" ::: "memory")
; #define PG8_BAR __builtin_amdgcn_s_barrier()
; #define PG8_SCHED __builtin_amdgcn_sched_barrier(0)
; template <class Epi, class Sched, bool ALIGN_EPI>
; __device__ __forceinline__ void gemm_phase(LAS unsigned char* lds, const Gemm g, const Sched& S, const Epi& E, const int tid) {
;     ...
;             PG8_LDA(At, 1, 1); PG8_STAGE(PG8_SB(1, 0), b3, voffB); PG8_STAGE(PG8_SB(1, 1), b3 + hstepB, voffB); PG8_STAGE(PG8_SA(1, 0), a3, voffA);
;             PG8_WAIT_V(8); PG8_WAIT_L(0); PG8_BAR; PG8_MMA(1, 0, At, B0); PG8_MMA(1, 1, At, B1); PG8_BAR; PG8_SCHED;
;         }
;         if constexpr (ALIGN_EPI) { if (wr == 0) PG8_BAR; }
	s_add_i32 s54, s74, s60
	v_lshl_add_u64 v[220:221], v[220:221], 0, s[2:3]
	s_mov_b32 m0, s54
	ds_read_b128 v[160:163], v193 offset:49152
	ds_read_b128 v[182:185], v193 offset:50176
	ds_read_b128 v[186:189], v193 offset:51200
	ds_read_b128 v[194:197], v193 offset:52224
	ds_read_b128 v[198:201], v193 offset:53248
	ds_read_b128 v[202:205], v193 offset:54272
	ds_read_b128 v[210:213], v193 offset:55296
	ds_read_b128 v[216:219], v193 offset:56320
	global_load_lds_dwordx4 v[220:221], off
	s_add_i32 m0, s54, 0x2000
	s_add_u32 s52, s52, 0x40080
	v_lshl_add_u64 v[220:221], v[222:223], 0, s[2:3]
	s_addc_u32 s53, s53, 0
	s_add_i32 s54, s75, s60
	global_load_lds_dwordx4 v[220:221], off
	v_lshl_add_u64 v[220:221], s[52:53], 0, v[164:165]
	s_mov_b32 m0, s54
	s_nop 0
	global_load_lds_dwordx4 v[220:221], off
	v_lshl_add_u64 v[220:221], s[52:53], 0, v[176:177]
	s_add_i32 m0, s54, 0x2000
	s_nop 0
	global_load_lds_dwordx4 v[220:221], off
	v_lshl_add_u64 v[220:221], v[224:225], 0, s[2:3]
	s_mov_b32 m0, s65
	s_nop 0
	global_load_lds_dwordx4 v[220:221], off
	v_lshl_add_u64 v[220:221], v[226:227], 0, s[2:3]
	s_mov_b32 m0, s66
	s_nop 0
	global_load_lds_dwordx4 v[220:221], off
	s_waitcnt vmcnt(8)
	s_waitcnt lgkmcnt(0)
	s_barrier
	s_setprio 1
	v_mfma_f32_16x16x32_bf16 v[52:55], v[64:67], v[160:163], v[52:55]
	v_mfma_f32_16x16x32_bf16 v[44:47], v[80:83], v[160:163], v[44:47]
	v_mfma_f32_16x16x32_bf16 v[36:39], v[64:67], v[186:189], v[36:39]
	v_mfma_f32_16x16x32_bf16 v[28:31], v[80:83], v[186:189], v[28:31]
	v_mfma_f32_16x16x32_bf16 v[24:27], v[64:67], v[198:201], v[24:27]
	v_mfma_f32_16x16x32_bf16 v[12:15], v[80:83], v[198:201], v[12:15]
	v_mfma_f32_16x16x32_bf16 v[16:19], v[64:67], v[210:213], v[16:19]
	v_mfma_f32_16x16x32_bf16 v[4:7], v[80:83], v[210:213], v[4:7]
	v_mfma_f32_16x16x32_bf16 v[52:55], v[68:71], v[182:185], v[52:55]
	v_mfma_f32_16x16x32_bf16 v[44:47], v[84:87], v[182:185], v[44:47]
	v_mfma_f32_16x16x32_bf16 v[36:39], v[68:71], v[194:197], v[36:39]
	v_mfma_f32_16x16x32_bf16 v[28:31], v[84:87], v[194:197], v[28:31]
	v_mfma_f32_16x16x32_bf16 v[24:27], v[68:71], v[202:205], v[24:27]
	v_mfma_f32_16x16x32_bf16 v[12:15], v[84:87], v[202:205], v[12:15]
	v_mfma_f32_16x16x32_bf16 v[16:19], v[68:71], v[216:219], v[16:19]
	v_mfma_f32_16x16x32_bf16 v[4:7], v[84:87], v[216:219], v[4:7]
	v_mfma_f32_16x16x32_bf16 v[60:63], v[88:91], v[160:163], v[60:63]
	v_mfma_f32_16x16x32_bf16 v[56:59], v[132:135], v[160:163], v[56:59]
	v_mfma_f32_16x16x32_bf16 v[48:51], v[88:91], v[186:189], v[48:51]
	v_mfma_f32_16x16x32_bf16 v[40:43], v[132:135], v[186:189], v[40:43]
	v_mfma_f32_16x16x32_bf16 v[32:35], v[88:91], v[198:201], v[32:35]
	v_mfma_f32_16x16x32_bf16 v[20:23], v[132:135], v[198:201], v[20:23]
	v_mfma_f32_16x16x32_bf16 v[8:11], v[88:91], v[210:213], v[8:11]
	v_mfma_f32_16x16x32_bf16 v[0:3], v[132:135], v[210:213], v[0:3]
	v_mfma_f32_16x16x32_bf16 v[60:63], v[92:95], v[182:185], v[60:63]
	v_mfma_f32_16x16x32_bf16 v[56:59], v[136:139], v[182:185], v[56:59]
	v_mfma_f32_16x16x32_bf16 v[48:51], v[92:95], v[194:197], v[48:51]
	v_mfma_f32_16x16x32_bf16 v[40:43], v[136:139], v[194:197], v[40:43]
	v_mfma_f32_16x16x32_bf16 v[32:35], v[92:95], v[202:205], v[32:35]
	v_mfma_f32_16x16x32_bf16 v[20:23], v[136:139], v[202:205], v[20:23]
	v_mfma_f32_16x16x32_bf16 v[8:11], v[92:95], v[216:219], v[8:11]
	v_mfma_f32_16x16x32_bf16 v[0:3], v[136:139], v[216:219], v[0:3]
	s_setprio 0
	s_barrier
	s_add_i32 s73, s73, 2
	s_add_u32 s50, s50, 0x100
	s_addc_u32 s51, s51, 0
	s_add_u32 s71, s71, 0x100
	s_addc_u32 s72, s72, 0
	s_cmp_gt_u32 s73, 13
	s_cbranch_scc0 .LBB0_71
	s_and_b64 vcc, exec, s[30:31]
	s_cbranch_vccz .LBB0_74
	s_barrier

; #define PG8_STAGE(bufoff, gbase, voff) do { _Pragma("unroll") for (int _i = 0; _i < 2; ++_i) \
;         __builtin_amdgcn_global_load_lds((const unsigned*)((const char*)(gbase) + (voff)[_i]), (LAS unsigned*)(lds + (bufoff) + ldsw + _i * 8192), 16, 0, 0); } while (0)
; #define PG8_LDA(dst, b, h) do { _Pragma("unroll") for (int m = 0; m < 4; ++m) _Pragma("unroll") for (int k = 0; k < 2; ++k) dst[m][k] = *(const LAS bf16x8*)(lds + PG8_SA(b, h) + aoff + m * 2048 + k * 1024); } while (0)
; #define PG8_LDB(dst, b, h) do { _Pragma("unroll") for (int n = 0; n < 2; ++n) _Pragma("unroll") for (int k = 0; k < 2; ++k) dst[n][k] = *(const LAS bf16x8*)(lds + PG8_SB(b, h) + boff + n * 2048 + k * 1024); } while (0)
; #define PG8_MMA(ai, bj, At, Bt) do { __builtin_amdgcn_s_setprio(1); _Pragma("unroll") for (int m = 0; m < 4; ++m) _Pragma("unroll") for (int n = 0; n < 2; ++n) _Pragma("unroll") for (int k = 0; k < 2; ++k) \
;         acc[ai][bj][m][n] = __builtin_amdgcn_mfma_f32_16x16x32_bf16(Bt[n][k], At[m][k], acc[ai][bj][m][n], 0, 0, 0); __builtin_amdgcn_s_setprio(0); } while (0)
; #define PG8_WAIT_V(n) asm volatile("s_waitcnt vmcnt(" #n ")" ::: "memory")
; #define PG8_WAIT_L(n) asm volatile("s_waitcnt lgkmcnt(" #n ")" ::: "memory")
; template <class Epi, class Sched, bool ALIGN_EPI>
; __device__ __forceinline__ void gemm_phase(LAS unsigned char* lds, const Gemm g, const Sched& S, const Epi& E, const int tid) {
;     ...
;         const bool has_next = S.next(ui + 1, nxt);
;         const char* nA = has_next ? (const char*)g.A + (size_t)nxt.pm * tstepA : cA; const char* nB = has_next ? (const char*)g.Bt + (size_t)nxt.pn * tstepB : cB;
;         for (int t = 0; t < nt; t += 2) {
;             const bool last = (t == nt - 2);
;             const char* a1 = cA + (size_t)(t + 1) * kstep;
;             const char* a2 = last ? nA : cA + (size_t)(t + 2) * kstep; const char* b2 = last ? nB : cB + (size_t)(t + 2) * kstep;
;             const char* a3 = a2 + kstep; const char* b3 = b2 + kstep;
;             PG8_LDB(B0, 0, 0); PG8_LDB(B1, 0, 1); PG8_SCHED; PG8_LDA(At, 0, 0); PG8_STAGE(PG8_SA(1, 1), a1 + hstepA, voffA);
;             PG8_WAIT_V(8); PG8_WAIT_L(0); PG8_BAR; PG8_MMA(0, 0, At, B0); PG8_MMA(0, 1, At, B1); PG8_BAR; PG8_SCHED;
;             PG8_LDA(At, 0, 1); PG8_STAGE(PG8_SB(0, 0), b2, voffB); PG8_STAGE(PG8_SB(0, 1), b2 + hstepB, voffB); PG8_STAGE(PG8_SA(0, 0), a2, voffA);
.LBB0_356:
	s_add_i32 s74, s28, 2
	s_add_u32 s10, s12, 0x100
	s_addc_u32 s11, s13, 0
	s_add_i32 s75, 0, 0x10000
	s_cmp_eq_u32 s67, s28
	s_cselect_b32 s29, s25, s11
	s_cselect_b32 s28, s24, s10
	s_cselect_b32 s77, s27, s73
	s_cselect_b32 s76, s26, s31
	s_add_i32 s78, 0, 0x14000
	v_add_u32_e32 v160, s75, v189
	v_add_u32_e32 v164, s78, v189
	ds_read_b128 v[128:131], v160
	ds_read_b128 v[132:135], v160 offset:1024
	ds_read_b128 v[156:159], v160 offset:2048
	ds_read_b128 v[160:163], v160 offset:3072
	ds_read_b128 v[172:175], v164
	ds_read_b128 v[176:179], v164 offset:1024
	ds_read_b128 v[190:193], v164 offset:2048
	ds_read_b128 v[194:197], v164 offset:3072
	v_lshl_add_u64 v[202:203], s[12:13], 0, v[142:143]
	s_add_i32 m0, s58, 0xc000
	ds_read_b128 v[198:201], v147
	ds_read_b128 v[216:219], v147 offset:1024
	ds_read_b128 v[220:223], v147 offset:2048
	ds_read_b128 v[224:227], v147 offset:3072
	ds_read_b128 v[228:231], v147 offset:4096
	ds_read_b128 v[232:235], v147 offset:5120
	ds_read_b128 v[236:239], v147 offset:6144
	ds_read_b128 v[240:243], v147 offset:7168
	global_load_lds_dwordx4 v[202:203], off
	v_lshl_add_u64 v[202:203], s[12:13], 0, v[144:145]
	s_add_i32 m0, s58, 0xe000
	s_nop 0
	global_load_lds_dwordx4 v[202:203], off
	s_waitcnt vmcnt(8)
	s_waitcnt lgkmcnt(0)
	s_barrier
	s_setprio 1
	v_mfma_f32_16x16x32_bf16 v[124:127], v[128:131], v[198:201], v[124:127]
	v_mfma_f32_16x16x32_bf16 v[120:123], v[156:159], v[198:201], v[120:123]
	v_mfma_f32_16x16x32_bf16 v[116:119], v[128:131], v[220:223], v[116:119]
	v_mfma_f32_16x16x32_bf16 v[112:115], v[156:159], v[220:223], v[112:115]
	v_mfma_f32_16x16x32_bf16 v[108:111], v[128:131], v[228:231], v[108:111]
	v_mfma_f32_16x16x32_bf16 v[104:107], v[156:159], v[228:231], v[104:107]
	v_mfma_f32_16x16x32_bf16 v[100:103], v[128:131], v[236:239], v[100:103]
	v_mfma_f32_16x16x32_bf16 v[96:99], v[156:159], v[236:239], v[96:99]
	v_mfma_f32_16x16x32_bf16 v[124:127], v[132:135], v[216:219], v[124:127]
	v_mfma_f32_16x16x32_bf16 v[120:123], v[160:163], v[216:219], v[120:123]
	v_mfma_f32_16x16x32_bf16 v[116:119], v[132:135], v[224:227], v[116:119]
	v_mfma_f32_16x16x32_bf16 v[112:115], v[160:163], v[224:227], v[112:115]
	v_mfma_f32_16x16x32_bf16 v[108:111], v[132:135], v[232:235], v[108:111]
	v_mfma_f32_16x16x32_bf16 v[104:107], v[160:163], v[232:235], v[104:107]
	v_mfma_f32_16x16x32_bf16 v[100:103], v[132:135], v[240:243], v[100:103]
	v_mfma_f32_16x16x32_bf16 v[96:99], v[160:163], v[240:243], v[96:99]
	v_mfma_f32_16x16x32_bf16 v[60:63], v[172:175], v[198:201], v[60:63]
	v_mfma_f32_16x16x32_bf16 v[56:59], v[190:193], v[198:201], v[56:59]
	v_mfma_f32_16x16x32_bf16 v[52:55], v[172:175], v[220:223], v[52:55]
	v_mfma_f32_16x16x32_bf16 v[48:51], v[190:193], v[220:223], v[48:51]
	v_mfma_f32_16x16x32_bf16 v[44:47], v[172:175], v[228:231], v[44:47]
	v_mfma_f32_16x16x32_bf16 v[40:43], v[190:193], v[228:231], v[40:43]
	v_mfma_f32_16x16x32_bf16 v[36:39], v[172:175], v[236:239], v[36:39]
	v_mfma_f32_16x16x32_bf16 v[32:35], v[190:193], v[236:239], v[32:35]
	v_mfma_f32_16x16x32_bf16 v[60:63], v[176:179], v[216:219], v[60:63]
	v_mfma_f32_16x16x32_bf16 v[56:59], v[194:197], v[216:219], v[56:59]
	v_mfma_f32_16x16x32_bf16 v[52:55], v[176:179], v[224:227], v[52:55]
	v_mfma_f32_16x16x32_bf16 v[48:51], v[194:197], v[224:227], v[48:51]
	v_mfma_f32_16x16x32_bf16 v[44:47], v[176:179], v[232:235], v[44:47]
	v_mfma_f32_16x16x32_bf16 v[40:43], v[194:197], v[232:235], v[40:43]
	v_mfma_f32_16x16x32_bf16 v[36:39], v[176:179], v[240:243], v[36:39]
	v_mfma_f32_16x16x32_bf16 v[32:35], v[194:197], v[240:243], v[32:35]
	s_setprio 0
	s_barrier
	s_add_i32 s12, s75, s57
	v_lshl_add_u64 v[202:203], s[76:77], 0, v[148:149]
	s_mov_b32 m0, s12
	ds_read_b128 v[198:201], v147 offset:16384
	ds_read_b128 v[216:219], v147 offset:17408
	ds_read_b128 v[220:223], v147 offset:18432
	ds_read_b128 v[224:227], v147 offset:19456
	ds_read_b128 v[228:231], v147 offset:20480
	ds_read_b128 v[232:235], v147 offset:21504
	ds_read_b128 v[236:239], v147 offset:22528
	ds_read_b128 v[240:243], v147 offset:23552
	global_load_lds_dwordx4 v[202:203], off
	s_add_i32 m0, s12, 0x2000
	s_add_u32 s12, s76, s55
	v_lshl_add_u64 v[204:205], s[76:77], 0, v[150:151]
	s_addc_u32 s13, s77, 0
	s_add_i32 s75, s78, s57
	global_load_lds_dwordx4 v[204:205], off
	v_lshl_add_u64 v[210:211], s[12:13], 0, v[148:149]
	s_mov_b32 m0, s75
	v_lshl_add_u64 v[212:213], s[12:13], 0, v[150:151]
	global_load_lds_dwordx4 v[210:211], off
	s_add_i32 m0, s75, 0x2000
	v_lshl_add_u64 v[244:245], s[28:29], 0, v[136:137]
	global_load_lds_dwordx4 v[212:213], off
	s_mov_b32 m0, s58
	v_lshl_add_u64 v[246:247], s[28:29], 0, v[138:139]
	global_load_lds_dwordx4 v[244:245], off
	s_mov_b32 m0, s59
	s_nop 0
	global_load_lds_dwordx4 v[246:247], off
	s_waitcnt vmcnt(8)
	s_waitcnt lgkmcnt(0)
	s_barrier
; #define PG8_STAGE(bufoff, gbase, voff) do { _Pragma("unroll") for (int _i = 0; _i < 2; ++_i) \
;         __builtin_amdgcn_global_load_lds((const unsigned*)((const char*)(gbase) + (voff)[_i]), (LAS unsigned*)(lds + (bufoff) + ldsw + _i * 8192), 16, 0, 0); } while (0)
; #define PG8_LDA(dst, b, h) do { _Pragma("unroll") for (int m = 0; m < 4; ++m) _Pragma("unroll") for (int k = 0; k < 2; ++k) dst[m][k] = *(const LAS bf16x8*)(lds + PG8_SA(b, h) + aoff + m * 2048 + k * 1024); } while (0)
; #define PG8_LDB(dst, b, h) do { _Pragma("unroll") for (int n = 0; n < 2; ++n) _Pragma("unroll") for (int k = 0; k < 2; ++k) dst[n][k] = *(const LAS bf16x8*)(lds + PG8_SB(b, h) + boff + n * 2048 + k * 1024); } while (0)
; #define PG8_MMA(ai, bj, At, Bt) do { __builtin_amdgcn_s_setprio(1); _Pragma("unroll") for (int m = 0; m < 4; ++m) _Pragma("unroll") for (int n = 0; n < 2; ++n) _Pragma("unroll") for (int k = 0; k < 2; ++k) \
;         acc[ai][bj][m][n] = __builtin_amdgcn_mfma_f32_16x16x32_bf16(Bt[n][k], At[m][k], acc[ai][bj][m][n], 0, 0, 0); __builtin_amdgcn_s_setprio(0); } while (0)
; #define PG8_WAIT_V(n) asm volatile("s_waitcnt vmcnt(" #n ")" ::: "memory")
; #define PG8_WAIT_L(n) asm volatile("s_waitcnt lgkmcnt(" #n ")" ::: "memory")
; #define PG8_BAR __builtin_amdgcn_s_barrier()
; #define PG8_SCHED __builtin_amdgcn_sched_barrier(0)
; template <class Epi, class Sched, bool ALIGN_EPI>
; __device__ __forceinline__ void gemm_phase(LAS unsigned char* lds, const Gemm g, const Sched& S, const Epi& E, const int tid) {
;     ...
;             PG8_WAIT_V(8); PG8_WAIT_L(0); PG8_BAR; PG8_MMA(1, 0, At, B0); PG8_MMA(1, 1, At, B1); PG8_BAR; PG8_SCHED;
;             PG8_LDB(B0, 1, 0); PG8_LDB(B1, 1, 1); PG8_SCHED; PG8_LDA(At, 1, 0); PG8_STAGE(PG8_SA(0, 1), a2 + hstepA, voffA);
;             PG8_WAIT_V(8); PG8_WAIT_L(0); PG8_BAR; PG8_MMA(0, 0, At, B0); PG8_MMA(0, 1, At, B1); PG8_BAR; PG8_SCHED;
	s_setprio 1
	v_mfma_f32_16x16x32_bf16 v[92:95], v[128:131], v[198:201], v[92:95]
	v_mfma_f32_16x16x32_bf16 v[88:91], v[156:159], v[198:201], v[88:91]
	v_mfma_f32_16x16x32_bf16 v[84:87], v[128:131], v[220:223], v[84:87]
	v_mfma_f32_16x16x32_bf16 v[80:83], v[156:159], v[220:223], v[80:83]
	v_mfma_f32_16x16x32_bf16 v[76:79], v[128:131], v[228:231], v[76:79]
	v_mfma_f32_16x16x32_bf16 v[72:75], v[156:159], v[228:231], v[72:75]
	v_mfma_f32_16x16x32_bf16 v[68:71], v[128:131], v[236:239], v[68:71]
	v_mfma_f32_16x16x32_bf16 v[64:67], v[156:159], v[236:239], v[64:67]
	v_mfma_f32_16x16x32_bf16 v[92:95], v[132:135], v[216:219], v[92:95]
	v_mfma_f32_16x16x32_bf16 v[88:91], v[160:163], v[216:219], v[88:91]
	v_mfma_f32_16x16x32_bf16 v[84:87], v[132:135], v[224:227], v[84:87]
	v_mfma_f32_16x16x32_bf16 v[80:83], v[160:163], v[224:227], v[80:83]
	v_mfma_f32_16x16x32_bf16 v[76:79], v[132:135], v[232:235], v[76:79]
	v_mfma_f32_16x16x32_bf16 v[72:75], v[160:163], v[232:235], v[72:75]
	v_mfma_f32_16x16x32_bf16 v[68:71], v[132:135], v[240:243], v[68:71]
	v_mfma_f32_16x16x32_bf16 v[64:67], v[160:163], v[240:243], v[64:67]
	v_mfma_f32_16x16x32_bf16 v[28:31], v[172:175], v[198:201], v[28:31]
	v_mfma_f32_16x16x32_bf16 v[24:27], v[190:193], v[198:201], v[24:27]
	v_mfma_f32_16x16x32_bf16 v[20:23], v[172:175], v[220:223], v[20:23]
	v_mfma_f32_16x16x32_bf16 v[16:19], v[190:193], v[220:223], v[16:19]
	v_mfma_f32_16x16x32_bf16 v[12:15], v[172:175], v[228:231], v[12:15]
	v_mfma_f32_16x16x32_bf16 v[8:11], v[190:193], v[228:231], v[8:11]
	v_mfma_f32_16x16x32_bf16 v[4:7], v[172:175], v[236:239], v[4:7]
	v_mfma_f32_16x16x32_bf16 v[0:3], v[190:193], v[236:239], v[0:3]
	v_mfma_f32_16x16x32_bf16 v[28:31], v[176:179], v[216:219], v[28:31]
	v_mfma_f32_16x16x32_bf16 v[24:27], v[194:197], v[216:219], v[24:27]
	v_mfma_f32_16x16x32_bf16 v[20:23], v[176:179], v[224:227], v[20:23]
	v_mfma_f32_16x16x32_bf16 v[16:19], v[194:197], v[224:227], v[16:19]
	v_mfma_f32_16x16x32_bf16 v[12:15], v[176:179], v[232:235], v[12:15]
	v_mfma_f32_16x16x32_bf16 v[8:11], v[194:197], v[232:235], v[8:11]
	v_mfma_f32_16x16x32_bf16 v[4:7], v[176:179], v[240:243], v[4:7]
	v_mfma_f32_16x16x32_bf16 v[0:3], v[194:197], v[240:243], v[0:3]
	s_setprio 0
	s_barrier
	s_add_i32 s75, 0, 0x18000
	s_add_i32 s76, 0, 0x1c000
	v_add_u32_e32 v160, s75, v189
	v_add_u32_e32 v164, s76, v189
	ds_read_b128 v[128:131], v160
	ds_read_b128 v[132:135], v160 offset:1024
	ds_read_b128 v[156:159], v160 offset:2048
	ds_read_b128 v[160:163], v160 offset:3072
	ds_read_b128 v[172:175], v164
	ds_read_b128 v[176:179], v164 offset:1024
	ds_read_b128 v[190:193], v164 offset:2048
	ds_read_b128 v[194:197], v164 offset:3072
	s_add_u32 s12, s28, 0x90000
	s_addc_u32 s13, s29, 0
	s_mov_b32 m0, s60
	v_lshl_add_u64 v[248:249], s[12:13], 0, v[136:137]
	ds_read_b128 v[198:201], v147 offset:32768
	ds_read_b128 v[216:219], v147 offset:33792
	ds_read_b128 v[220:223], v147 offset:34816
	ds_read_b128 v[224:227], v147 offset:35840
	ds_read_b128 v[228:231], v147 offset:36864
	ds_read_b128 v[232:235], v147 offset:37888
	ds_read_b128 v[236:239], v147 offset:38912
	ds_read_b128 v[240:243], v147 offset:39936
	global_load_lds_dwordx4 v[248:249], off
	v_lshl_add_u64 v[248:249], s[12:13], 0, v[138:139]
	s_mov_b32 m0, s61
	s_nop 0
	global_load_lds_dwordx4 v[248:249], off
	s_waitcnt vmcnt(8)
	s_waitcnt lgkmcnt(0)
	s_barrier
	s_setprio 1
	v_mfma_f32_16x16x32_bf16 v[124:127], v[128:131], v[198:201], v[124:127]
	v_mfma_f32_16x16x32_bf16 v[120:123], v[156:159], v[198:201], v[120:123]
	v_mfma_f32_16x16x32_bf16 v[116:119], v[128:131], v[220:223], v[116:119]
	v_mfma_f32_16x16x32_bf16 v[112:115], v[156:159], v[220:223], v[112:115]
	v_mfma_f32_16x16x32_bf16 v[108:111], v[128:131], v[228:231], v[108:111]
	v_mfma_f32_16x16x32_bf16 v[104:107], v[156:159], v[228:231], v[104:107]
	v_mfma_f32_16x16x32_bf16 v[100:103], v[128:131], v[236:239], v[100:103]
	v_mfma_f32_16x16x32_bf16 v[96:99], v[156:159], v[236:239], v[96:99]
	v_mfma_f32_16x16x32_bf16 v[124:127], v[132:135], v[216:219], v[124:127]
	v_mfma_f32_16x16x32_bf16 v[120:123], v[160:163], v[216:219], v[120:123]
	v_mfma_f32_16x16x32_bf16 v[116:119], v[132:135], v[224:227], v[116:119]
	v_mfma_f32_16x16x32_bf16 v[112:115], v[160:163], v[224:227], v[112:115]
	v_mfma_f32_16x16x32_bf16 v[108:111], v[132:135], v[232:235], v[108:111]
	v_mfma_f32_16x16x32_bf16 v[104:107], v[160:163], v[232:235], v[104:107]
	v_mfma_f32_16x16x32_bf16 v[100:103], v[132:135], v[240:243], v[100:103]
	v_mfma_f32_16x16x32_bf16 v[96:99], v[160:163], v[240:243], v[96:99]
	v_mfma_f32_16x16x32_bf16 v[60:63], v[172:175], v[198:201], v[60:63]
	v_mfma_f32_16x16x32_bf16 v[56:59], v[190:193], v[198:201], v[56:59]
	v_mfma_f32_16x16x32_bf16 v[52:55], v[172:175], v[220:223], v[52:55]
	v_mfma_f32_16x16x32_bf16 v[48:51], v[190:193], v[220:223], v[48:51]
	v_mfma_f32_16x16x32_bf16 v[44:47], v[172:175], v[228:231], v[44:47]
	v_mfma_f32_16x16x32_bf16 v[40:43], v[190:193], v[228:231], v[40:43]
	v_mfma_f32_16x16x32_bf16 v[36:39], v[172:175], v[236:239], v[36:39]
	v_mfma_f32_16x16x32_bf16 v[32:35], v[190:193], v[236:239], v[32:35]
	v_mfma_f32_16x16x32_bf16 v[60:63], v[176:179], v[216:219], v[60:63]
	v_mfma_f32_16x16x32_bf16 v[56:59], v[194:197], v[216:219], v[56:59]
	v_mfma_f32_16x16x32_bf16 v[52:55], v[176:179], v[224:227], v[52:55]
	v_mfma_f32_16x16x32_bf16 v[48:51], v[194:197], v[224:227], v[48:51]
	v_mfma_f32_16x16x32_bf16 v[44:47], v[176:179], v[232:235], v[44:47]
	v_mfma_f32_16x16x32_bf16 v[40:43], v[194:197], v[232:235], v[40:43]
	v_mfma_f32_16x16x32_bf16 v[36:39], v[176:179], v[240:243], v[36:39]
	v_mfma_f32_16x16x32_bf16 v[32:35], v[194:197], v[240:243], v[32:35]
	s_setprio 0
	s_barrier
; #define PG8_STAGE(bufoff, gbase, voff) do { _Pragma("unroll") for (int _i = 0; _i < 2; ++_i) \
;         __builtin_amdgcn_global_load_lds((const unsigned*)((const char*)(gbase) + (voff)[_i]), (LAS unsigned*)(lds + (bufoff) + ldsw + _i * 8192), 16, 0, 0); } while (0)
; #define PG8_LDA(dst, b, h) do { _Pragma("unroll") for (int m = 0; m < 4; ++m) _Pragma("unroll") for (int k = 0; k < 2; ++k) dst[m][k] = *(const LAS bf16x8*)(lds + PG8_SA(b, h) + aoff + m * 2048 + k * 1024); } while (0)
; #define PG8_MMA(ai, bj, At, Bt) do { __builtin_amdgcn_s_setprio(1); _Pragma("unroll") for (int m = 0; m < 4; ++m) _Pragma("unroll") for (int n = 0; n < 2; ++n) _Pragma("unroll") for (int k = 0; k < 2; ++k) \
;         acc[ai][bj][m][n] = __builtin_amdgcn_mfma_f32_16x16x32_bf16(Bt[n][k], At[m][k], acc[ai][bj][m][n], 0, 0, 0); __builtin_amdgcn_s_setprio(0); } while (0)
; #define PG8_WAIT_V(n) asm volatile("s_waitcnt vmcnt(" #n ")" ::: "memory")
; #define PG8_WAIT_L(n) asm volatile("s_waitcnt lgkmcnt(" #n ")" ::: "memory")
; #define PG8_BAR __builtin_amdgcn_s_barrier()
; #define PG8_SCHED __builtin_amdgcn_sched_barrier(0)
; template <class Epi, class Sched, bool ALIGN_EPI>
; __device__ __forceinline__ void gemm_phase(LAS unsigned char* lds, const Gemm g, const Sched& S, const Epi& E, const int tid) {
;     ...
;             PG8_LDA(At, 1, 1); PG8_STAGE(PG8_SB(1, 0), b3, voffB); PG8_STAGE(PG8_SB(1, 1), b3 + hstepB, voffB); PG8_STAGE(PG8_SA(1, 0), a3, voffA);
;             PG8_WAIT_V(8); PG8_WAIT_L(0); PG8_BAR; PG8_MMA(1, 0, At, B0); PG8_MMA(1, 1, At, B1); PG8_BAR; PG8_SCHED;
;         }
;         if constexpr (ALIGN_EPI) { if (wr == 0) PG8_BAR; }
	s_add_i32 s12, s75, s57
	v_lshl_add_u64 v[202:203], v[202:203], 0, s[2:3]
	s_mov_b32 m0, s12
	ds_read_b128 v[198:201], v147 offset:49152
	ds_read_b128 v[216:219], v147 offset:50176
	ds_read_b128 v[220:223], v147 offset:51200
	ds_read_b128 v[224:227], v147 offset:52224
	ds_read_b128 v[228:231], v147 offset:53248
	ds_read_b128 v[232:235], v147 offset:54272
	ds_read_b128 v[236:239], v147 offset:55296
	ds_read_b128 v[240:243], v147 offset:56320
	global_load_lds_dwordx4 v[202:203], off
	v_lshl_add_u64 v[202:203], v[204:205], 0, s[2:3]
	s_add_i32 m0, s12, 0x2000
	s_add_i32 s12, s76, s57
	global_load_lds_dwordx4 v[202:203], off
	v_lshl_add_u64 v[202:203], v[210:211], 0, s[2:3]
	s_mov_b32 m0, s12
	s_nop 0
	global_load_lds_dwordx4 v[202:203], off
	v_lshl_add_u64 v[202:203], v[212:213], 0, s[2:3]
	s_add_i32 m0, s12, 0x2000
	s_nop 0
	global_load_lds_dwordx4 v[202:203], off
	v_lshl_add_u64 v[202:203], v[244:245], 0, s[2:3]
	s_mov_b32 m0, s62
	s_nop 0
	global_load_lds_dwordx4 v[202:203], off
	v_lshl_add_u64 v[202:203], v[246:247], 0, s[2:3]
	s_mov_b32 m0, s63
	s_nop 0
	global_load_lds_dwordx4 v[202:203], off
	s_waitcnt vmcnt(8)
	s_waitcnt lgkmcnt(0)
	s_barrier
	s_setprio 1
	v_mfma_f32_16x16x32_bf16 v[92:95], v[128:131], v[198:201], v[92:95]
	v_mfma_f32_16x16x32_bf16 v[88:91], v[156:159], v[198:201], v[88:91]
	v_mfma_f32_16x16x32_bf16 v[84:87], v[128:131], v[220:223], v[84:87]
	v_mfma_f32_16x16x32_bf16 v[80:83], v[156:159], v[220:223], v[80:83]
	v_mfma_f32_16x16x32_bf16 v[76:79], v[128:131], v[228:231], v[76:79]
	v_mfma_f32_16x16x32_bf16 v[72:75], v[156:159], v[228:231], v[72:75]
	v_mfma_f32_16x16x32_bf16 v[68:71], v[128:131], v[236:239], v[68:71]
	v_mfma_f32_16x16x32_bf16 v[64:67], v[156:159], v[236:239], v[64:67]
	v_mfma_f32_16x16x32_bf16 v[92:95], v[132:135], v[216:219], v[92:95]
	v_mfma_f32_16x16x32_bf16 v[88:91], v[160:163], v[216:219], v[88:91]
	v_mfma_f32_16x16x32_bf16 v[84:87], v[132:135], v[224:227], v[84:87]
	v_mfma_f32_16x16x32_bf16 v[80:83], v[160:163], v[224:227], v[80:83]
	v_mfma_f32_16x16x32_bf16 v[76:79], v[132:135], v[232:235], v[76:79]
	v_mfma_f32_16x16x32_bf16 v[72:75], v[160:163], v[232:235], v[72:75]
	v_mfma_f32_16x16x32_bf16 v[68:71], v[132:135], v[240:243], v[68:71]
	v_mfma_f32_16x16x32_bf16 v[64:67], v[160:163], v[240:243], v[64:67]
	v_mfma_f32_16x16x32_bf16 v[28:31], v[172:175], v[198:201], v[28:31]
	v_mfma_f32_16x16x32_bf16 v[24:27], v[190:193], v[198:201], v[24:27]
	v_mfma_f32_16x16x32_bf16 v[20:23], v[172:175], v[220:223], v[20:23]
	v_mfma_f32_16x16x32_bf16 v[16:19], v[190:193], v[220:223], v[16:19]
	v_mfma_f32_16x16x32_bf16 v[12:15], v[172:175], v[228:231], v[12:15]
	v_mfma_f32_16x16x32_bf16 v[8:11], v[190:193], v[228:231], v[8:11]
	v_mfma_f32_16x16x32_bf16 v[4:7], v[172:175], v[236:239], v[4:7]
	v_mfma_f32_16x16x32_bf16 v[0:3], v[190:193], v[236:239], v[0:3]
	v_mfma_f32_16x16x32_bf16 v[28:31], v[176:179], v[216:219], v[28:31]
	v_mfma_f32_16x16x32_bf16 v[24:27], v[194:197], v[216:219], v[24:27]
	v_mfma_f32_16x16x32_bf16 v[20:23], v[176:179], v[224:227], v[20:23]
	v_mfma_f32_16x16x32_bf16 v[16:19], v[194:197], v[224:227], v[16:19]
	v_mfma_f32_16x16x32_bf16 v[12:15], v[176:179], v[232:235], v[12:15]
	v_mfma_f32_16x16x32_bf16 v[8:11], v[194:197], v[232:235], v[8:11]
	v_mfma_f32_16x16x32_bf16 v[4:7], v[176:179], v[240:243], v[4:7]
	v_mfma_f32_16x16x32_bf16 v[0:3], v[194:197], v[240:243], v[0:3]
	s_setprio 0
	s_barrier
	s_add_u32 s31, s31, 0x100
	s_addc_u32 s73, s73, 0
	s_cmp_ge_u32 s74, s65
	s_mov_b64 s[12:13], s[10:11]
	s_mov_b32 s28, s74
	s_cbranch_scc0 .LBB0_356
	s_and_b64 vcc, exec, s[22:23]
	s_cbranch_vccz .LBB0_359
	s_barrier

; #define PG8_STAGE(bufoff, gbase, voff) do { _Pragma("unroll") for (int _i = 0; _i < 2; ++_i) \
;         __builtin_amdgcn_global_load_lds((const unsigned*)((const char*)(gbase) + (voff)[_i]), (LAS unsigned*)(lds + (bufoff) + ldsw + _i * 8192), 16, 0, 0); } while (0)
; #define PG8_LDA(dst, b, h) do { _Pragma("unroll") for (int m = 0; m < 4; ++m) _Pragma("unroll") for (int k = 0; k < 2; ++k) dst[m][k] = *(const LAS bf16x8*)(lds + PG8_SA(b, h) + aoff + m * 2048 + k * 1024); } while (0)
; #define PG8_LDB(dst, b, h) do { _Pragma("unroll") for (int n = 0; n < 2; ++n) _Pragma("unroll") for (int k = 0; k < 2; ++k) dst[n][k] = *(const LAS bf16x8*)(lds + PG8_SB(b, h) + boff + n * 2048 + k * 1024); } while (0)
; #define PG8_MMA(ai, bj, At, Bt) do { __builtin_amdgcn_s_setprio(1); _Pragma("unroll") for (int m = 0; m < 4; ++m) _Pragma("unroll") for (int n = 0; n < 2; ++n) _Pragma("unroll") for (int k = 0; k < 2; ++k) \
;         acc[ai][bj][m][n] = __builtin_amdgcn_mfma_f32_16x16x32_bf16(Bt[n][k], At[m][k], acc[ai][bj][m][n], 0, 0, 0); __builtin_amdgcn_s_setprio(0); } while (0)
; #define PG8_WAIT_V(n) asm volatile("s_waitcnt vmcnt(" #n ")" ::: "memory")
; #define PG8_WAIT_L(n) asm volatile("s_waitcnt lgkmcnt(" #n ")" ::: "memory")
; template <class Epi, class Sched, bool ALIGN_EPI>
; __device__ __forceinline__ void gemm_phase(LAS unsigned char* lds, const Gemm g, const Sched& S, const Epi& E, const int tid) {
;     ...
;         const bool has_next = S.next(ui + 1, nxt);
;         const char* nA = has_next ? (const char*)g.A + (size_t)nxt.pm * tstepA : cA; const char* nB = has_next ? (const char*)g.Bt + (size_t)nxt.pn * tstepB : cB;
;         for (int t = 0; t < nt; t += 2) {
;             const bool last = (t == nt - 2);
;             const char* a1 = cA + (size_t)(t + 1) * kstep;
;             const char* a2 = last ? nA : cA + (size_t)(t + 2) * kstep; const char* b2 = last ? nB : cB + (size_t)(t + 2) * kstep;
;             const char* a3 = a2 + kstep; const char* b3 = b2 + kstep;
;             PG8_LDB(B0, 0, 0); PG8_LDB(B1, 0, 1); PG8_SCHED; PG8_LDA(At, 0, 0); PG8_STAGE(PG8_SA(1, 1), a1 + hstepA, voffA);
;             PG8_WAIT_V(8); PG8_WAIT_L(0); PG8_BAR; PG8_MMA(0, 0, At, B0); PG8_MMA(0, 1, At, B1); PG8_BAR; PG8_SCHED;
;             PG8_LDA(At, 0, 1); PG8_STAGE(PG8_SB(0, 0), b2, voffB); PG8_STAGE(PG8_SB(0, 1), b2 + hstepB, voffB); PG8_STAGE(PG8_SA(0, 0), a2, voffA);
.LBB0_615:
	s_add_i32 s52, s24, 2
	s_add_u32 s53, s22, 0x80
	s_addc_u32 s25, s23, 0
	s_add_i32 s56, 0, 0x10000
	s_cmp_eq_u32 s43, s24
	s_cselect_b32 s25, s9, s25
	s_cselect_b32 s24, s8, s53
	v_add_u32_e32 v143, s56, v141
	s_cselect_b32 s55, s21, s51
	s_cselect_b32 s54, s20, s50
	s_add_i32 s53, 0, 0x14000
	ds_read_b128 v[144:147], v143
	ds_read_b128 v[148:151], v143 offset:1024
	ds_read_b128 v[152:155], v143 offset:2048
	ds_read_b128 v[156:159], v143 offset:3072
	v_add_u32_e32 v143, s53, v141
	ds_read_b128 v[160:163], v143
	ds_read_b128 v[170:173], v143 offset:1024
	ds_read_b128 v[174:177], v143 offset:2048
	ds_read_b128 v[178:181], v143 offset:3072
	v_lshl_add_u64 v[202:203], s[22:23], 0, v[136:137]
	s_add_i32 m0, s35, 0xc000
	ds_read_b128 v[182:185], v142
	ds_read_b128 v[186:189], v142 offset:1024
	ds_read_b128 v[190:193], v142 offset:2048
	ds_read_b128 v[194:197], v142 offset:3072
	ds_read_b128 v[198:201], v142 offset:4096
	ds_read_b128 v[216:219], v142 offset:5120
	ds_read_b128 v[220:223], v142 offset:6144
	ds_read_b128 v[224:227], v142 offset:7168
	global_load_lds_dwordx4 v[202:203], off
	v_lshl_add_u64 v[202:203], s[22:23], 0, v[138:139]
	s_add_i32 m0, s35, 0xe000
	s_nop 0
	global_load_lds_dwordx4 v[202:203], off
	s_waitcnt vmcnt(8)
	s_waitcnt lgkmcnt(0)
	s_barrier
	s_setprio 1
	v_mfma_f32_16x16x32_bf16 v[124:127], v[144:147], v[182:185], v[124:127]
	v_mfma_f32_16x16x32_bf16 v[120:123], v[152:155], v[182:185], v[120:123]
	v_mfma_f32_16x16x32_bf16 v[116:119], v[144:147], v[190:193], v[116:119]
	v_mfma_f32_16x16x32_bf16 v[112:115], v[152:155], v[190:193], v[112:115]
	v_mfma_f32_16x16x32_bf16 v[108:111], v[144:147], v[198:201], v[108:111]
	v_mfma_f32_16x16x32_bf16 v[104:107], v[152:155], v[198:201], v[104:107]
	v_mfma_f32_16x16x32_bf16 v[100:103], v[144:147], v[220:223], v[100:103]
	v_mfma_f32_16x16x32_bf16 v[96:99], v[152:155], v[220:223], v[96:99]
	v_mfma_f32_16x16x32_bf16 v[124:127], v[148:151], v[186:189], v[124:127]
	v_mfma_f32_16x16x32_bf16 v[120:123], v[156:159], v[186:189], v[120:123]
	v_mfma_f32_16x16x32_bf16 v[116:119], v[148:151], v[194:197], v[116:119]
	v_mfma_f32_16x16x32_bf16 v[112:115], v[156:159], v[194:197], v[112:115]
	v_mfma_f32_16x16x32_bf16 v[108:111], v[148:151], v[216:219], v[108:111]
	v_mfma_f32_16x16x32_bf16 v[104:107], v[156:159], v[216:219], v[104:107]
	v_mfma_f32_16x16x32_bf16 v[100:103], v[148:151], v[224:227], v[100:103]
	v_mfma_f32_16x16x32_bf16 v[96:99], v[156:159], v[224:227], v[96:99]
	v_mfma_f32_16x16x32_bf16 v[68:71], v[160:163], v[182:185], v[68:71]
	v_mfma_f32_16x16x32_bf16 v[64:67], v[174:177], v[182:185], v[64:67]
	v_mfma_f32_16x16x32_bf16 v[52:55], v[160:163], v[190:193], v[52:55]
	v_mfma_f32_16x16x32_bf16 v[48:51], v[174:177], v[190:193], v[48:51]
	v_mfma_f32_16x16x32_bf16 v[44:47], v[160:163], v[198:201], v[44:47]
	v_mfma_f32_16x16x32_bf16 v[40:43], v[174:177], v[198:201], v[40:43]
	v_mfma_f32_16x16x32_bf16 v[36:39], v[160:163], v[220:223], v[36:39]
	v_mfma_f32_16x16x32_bf16 v[32:35], v[174:177], v[220:223], v[32:35]
	v_mfma_f32_16x16x32_bf16 v[68:71], v[170:173], v[186:189], v[68:71]
	v_mfma_f32_16x16x32_bf16 v[64:67], v[178:181], v[186:189], v[64:67]
	v_mfma_f32_16x16x32_bf16 v[52:55], v[170:173], v[194:197], v[52:55]
	v_mfma_f32_16x16x32_bf16 v[48:51], v[178:181], v[194:197], v[48:51]
	v_mfma_f32_16x16x32_bf16 v[44:47], v[170:173], v[216:219], v[44:47]
	v_mfma_f32_16x16x32_bf16 v[40:43], v[178:181], v[216:219], v[40:43]
	v_mfma_f32_16x16x32_bf16 v[36:39], v[170:173], v[224:227], v[36:39]
	v_mfma_f32_16x16x32_bf16 v[32:35], v[178:181], v[224:227], v[32:35]
	s_setprio 0
	s_barrier
	s_add_i32 s56, s56, s29
	v_lshl_add_u64 v[202:203], s[54:55], 0, v[164:165]
	s_mov_b32 m0, s56
	ds_read_b128 v[182:185], v142 offset:16384
	ds_read_b128 v[186:189], v142 offset:17408
	ds_read_b128 v[190:193], v142 offset:18432
	ds_read_b128 v[194:197], v142 offset:19456
	ds_read_b128 v[198:201], v142 offset:20480
	ds_read_b128 v[216:219], v142 offset:21504
	ds_read_b128 v[220:223], v142 offset:22528
	ds_read_b128 v[224:227], v142 offset:23552
	global_load_lds_dwordx4 v[202:203], off
	s_add_i32 m0, s56, 0x2000
	v_lshl_add_u64 v[204:205], s[54:55], 0, v[128:129]
	s_add_u32 s54, s54, s94
	s_addc_u32 s55, s55, 0
	s_add_i32 s53, s53, s29
	global_load_lds_dwordx4 v[204:205], off
	v_lshl_add_u64 v[210:211], s[54:55], 0, v[164:165]
	s_mov_b32 m0, s53
	v_lshl_add_u64 v[212:213], s[54:55], 0, v[128:129]
	global_load_lds_dwordx4 v[210:211], off
	s_add_i32 m0, s53, 0x2000
	v_lshl_add_u64 v[228:229], s[24:25], 0, v[132:133]
	global_load_lds_dwordx4 v[212:213], off
	s_mov_b32 m0, s35
	v_lshl_add_u64 v[230:231], s[24:25], 0, v[130:131]
	global_load_lds_dwordx4 v[228:229], off
	s_mov_b32 m0, s36
	s_nop 0
	global_load_lds_dwordx4 v[230:231], off
	s_waitcnt vmcnt(8)
	s_waitcnt lgkmcnt(0)
	s_barrier
; #define PG8_STAGE(bufoff, gbase, voff) do { _Pragma("unroll") for (int _i = 0; _i < 2; ++_i) \
;         __builtin_amdgcn_global_load_lds((const unsigned*)((const char*)(gbase) + (voff)[_i]), (LAS unsigned*)(lds + (bufoff) + ldsw + _i * 8192), 16, 0, 0); } while (0)
; #define PG8_LDA(dst, b, h) do { _Pragma("unroll") for (int m = 0; m < 4; ++m) _Pragma("unroll") for (int k = 0; k < 2; ++k) dst[m][k] = *(const LAS bf16x8*)(lds + PG8_SA(b, h) + aoff + m * 2048 + k * 1024); } while (0)
; #define PG8_LDB(dst, b, h) do { _Pragma("unroll") for (int n = 0; n < 2; ++n) _Pragma("unroll") for (int k = 0; k < 2; ++k) dst[n][k] = *(const LAS bf16x8*)(lds + PG8_SB(b, h) + boff + n * 2048 + k * 1024); } while (0)
; #define PG8_MMA(ai, bj, At, Bt) do { __builtin_amdgcn_s_setprio(1); _Pragma("unroll") for (int m = 0; m < 4; ++m) _Pragma("unroll") for (int n = 0; n < 2; ++n) _Pragma("unroll") for (int k = 0; k < 2; ++k) \
;         acc[ai][bj][m][n] = __builtin_amdgcn_mfma_f32_16x16x32_bf16(Bt[n][k], At[m][k], acc[ai][bj][m][n], 0, 0, 0); __builtin_amdgcn_s_setprio(0); } while (0)
; #define PG8_WAIT_V(n) asm volatile("s_waitcnt vmcnt(" #n ")" ::: "memory")
; #define PG8_WAIT_L(n) asm volatile("s_waitcnt lgkmcnt(" #n ")" ::: "memory")
; #define PG8_BAR __builtin_amdgcn_s_barrier()
; #define PG8_SCHED __builtin_amdgcn_sched_barrier(0)
; template <class Epi, class Sched, bool ALIGN_EPI>
; __device__ __forceinline__ void gemm_phase(LAS unsigned char* lds, const Gemm g, const Sched& S, const Epi& E, const int tid) {
;     ...
;             PG8_WAIT_V(8); PG8_WAIT_L(0); PG8_BAR; PG8_MMA(1, 0, At, B0); PG8_MMA(1, 1, At, B1); PG8_BAR; PG8_SCHED;
;             PG8_LDB(B0, 1, 0); PG8_LDB(B1, 1, 1); PG8_SCHED; PG8_LDA(At, 1, 0); PG8_STAGE(PG8_SA(0, 1), a2 + hstepA, voffA);
;             PG8_WAIT_V(8); PG8_WAIT_L(0); PG8_BAR; PG8_MMA(0, 0, At, B0); PG8_MMA(0, 1, At, B1); PG8_BAR; PG8_SCHED;
	s_setprio 1
	v_mfma_f32_16x16x32_bf16 v[92:95], v[144:147], v[182:185], v[92:95]
	v_mfma_f32_16x16x32_bf16 v[88:91], v[152:155], v[182:185], v[88:91]
	v_mfma_f32_16x16x32_bf16 v[84:87], v[144:147], v[190:193], v[84:87]
	v_mfma_f32_16x16x32_bf16 v[80:83], v[152:155], v[190:193], v[80:83]
	v_mfma_f32_16x16x32_bf16 v[76:79], v[144:147], v[198:201], v[76:79]
	v_mfma_f32_16x16x32_bf16 v[72:75], v[152:155], v[198:201], v[72:75]
	v_mfma_f32_16x16x32_bf16 v[60:63], v[144:147], v[220:223], v[60:63]
	v_mfma_f32_16x16x32_bf16 v[56:59], v[152:155], v[220:223], v[56:59]
	v_mfma_f32_16x16x32_bf16 v[92:95], v[148:151], v[186:189], v[92:95]
	v_mfma_f32_16x16x32_bf16 v[88:91], v[156:159], v[186:189], v[88:91]
	v_mfma_f32_16x16x32_bf16 v[84:87], v[148:151], v[194:197], v[84:87]
	v_mfma_f32_16x16x32_bf16 v[80:83], v[156:159], v[194:197], v[80:83]
	v_mfma_f32_16x16x32_bf16 v[76:79], v[148:151], v[216:219], v[76:79]
	v_mfma_f32_16x16x32_bf16 v[72:75], v[156:159], v[216:219], v[72:75]
	v_mfma_f32_16x16x32_bf16 v[60:63], v[148:151], v[224:227], v[60:63]
	v_mfma_f32_16x16x32_bf16 v[56:59], v[156:159], v[224:227], v[56:59]
	v_mfma_f32_16x16x32_bf16 v[28:31], v[160:163], v[182:185], v[28:31]
	v_mfma_f32_16x16x32_bf16 v[24:27], v[174:177], v[182:185], v[24:27]
	v_mfma_f32_16x16x32_bf16 v[20:23], v[160:163], v[190:193], v[20:23]
	v_mfma_f32_16x16x32_bf16 v[16:19], v[174:177], v[190:193], v[16:19]
	v_mfma_f32_16x16x32_bf16 v[12:15], v[160:163], v[198:201], v[12:15]
	v_mfma_f32_16x16x32_bf16 v[8:11], v[174:177], v[198:201], v[8:11]
	v_mfma_f32_16x16x32_bf16 v[4:7], v[160:163], v[220:223], v[4:7]
	v_mfma_f32_16x16x32_bf16 v[0:3], v[174:177], v[220:223], v[0:3]
	v_mfma_f32_16x16x32_bf16 v[28:31], v[170:173], v[186:189], v[28:31]
	v_mfma_f32_16x16x32_bf16 v[24:27], v[178:181], v[186:189], v[24:27]
	v_mfma_f32_16x16x32_bf16 v[20:23], v[170:173], v[194:197], v[20:23]
	v_mfma_f32_16x16x32_bf16 v[16:19], v[178:181], v[194:197], v[16:19]
	v_mfma_f32_16x16x32_bf16 v[12:15], v[170:173], v[216:219], v[12:15]
	v_mfma_f32_16x16x32_bf16 v[8:11], v[178:181], v[216:219], v[8:11]
	v_mfma_f32_16x16x32_bf16 v[4:7], v[170:173], v[224:227], v[4:7]
	v_mfma_f32_16x16x32_bf16 v[0:3], v[178:181], v[224:227], v[0:3]
	s_setprio 0
	s_barrier
	s_add_i32 s53, 0, 0x18000
	v_add_u32_e32 v143, s53, v141
	s_add_i32 s54, 0, 0x1c000
	ds_read_b128 v[144:147], v143
	ds_read_b128 v[148:151], v143 offset:1024
	ds_read_b128 v[152:155], v143 offset:2048
	ds_read_b128 v[156:159], v143 offset:3072
	v_add_u32_e32 v143, s54, v141
	ds_read_b128 v[160:163], v143
	ds_read_b128 v[170:173], v143 offset:1024
	ds_read_b128 v[174:177], v143 offset:2048
	ds_read_b128 v[178:181], v143 offset:3072
	s_add_u32 s24, s24, s94
	s_addc_u32 s25, s25, 0
	s_mov_b32 m0, s37
	v_lshl_add_u64 v[232:233], s[24:25], 0, v[132:133]
	ds_read_b128 v[182:185], v142 offset:32768
	ds_read_b128 v[186:189], v142 offset:33792
	ds_read_b128 v[190:193], v142 offset:34816
	ds_read_b128 v[194:197], v142 offset:35840
	ds_read_b128 v[198:201], v142 offset:36864
	ds_read_b128 v[216:219], v142 offset:37888
	ds_read_b128 v[220:223], v142 offset:38912
	ds_read_b128 v[224:227], v142 offset:39936
	global_load_lds_dwordx4 v[232:233], off
	v_lshl_add_u64 v[232:233], s[24:25], 0, v[130:131]
	s_mov_b32 m0, s38
	s_nop 0
	global_load_lds_dwordx4 v[232:233], off
	s_waitcnt vmcnt(8)
	s_waitcnt lgkmcnt(0)
	s_barrier
	s_setprio 1
	v_mfma_f32_16x16x32_bf16 v[124:127], v[144:147], v[182:185], v[124:127]
	v_mfma_f32_16x16x32_bf16 v[120:123], v[152:155], v[182:185], v[120:123]
	v_mfma_f32_16x16x32_bf16 v[116:119], v[144:147], v[190:193], v[116:119]
	v_mfma_f32_16x16x32_bf16 v[112:115], v[152:155], v[190:193], v[112:115]
	v_mfma_f32_16x16x32_bf16 v[108:111], v[144:147], v[198:201], v[108:111]
	v_mfma_f32_16x16x32_bf16 v[104:107], v[152:155], v[198:201], v[104:107]
	v_mfma_f32_16x16x32_bf16 v[100:103], v[144:147], v[220:223], v[100:103]
	v_mfma_f32_16x16x32_bf16 v[96:99], v[152:155], v[220:223], v[96:99]
	v_mfma_f32_16x16x32_bf16 v[124:127], v[148:151], v[186:189], v[124:127]
	v_mfma_f32_16x16x32_bf16 v[120:123], v[156:159], v[186:189], v[120:123]
	v_mfma_f32_16x16x32_bf16 v[116:119], v[148:151], v[194:197], v[116:119]
	v_mfma_f32_16x16x32_bf16 v[112:115], v[156:159], v[194:197], v[112:115]
	v_mfma_f32_16x16x32_bf16 v[108:111], v[148:151], v[216:219], v[108:111]
	v_mfma_f32_16x16x32_bf16 v[104:107], v[156:159], v[216:219], v[104:107]
	v_mfma_f32_16x16x32_bf16 v[100:103], v[148:151], v[224:227], v[100:103]
	v_mfma_f32_16x16x32_bf16 v[96:99], v[156:159], v[224:227], v[96:99]
	v_mfma_f32_16x16x32_bf16 v[68:71], v[160:163], v[182:185], v[68:71]
	v_mfma_f32_16x16x32_bf16 v[64:67], v[174:177], v[182:185], v[64:67]
	v_mfma_f32_16x16x32_bf16 v[52:55], v[160:163], v[190:193], v[52:55]
	v_mfma_f32_16x16x32_bf16 v[48:51], v[174:177], v[190:193], v[48:51]
	v_mfma_f32_16x16x32_bf16 v[44:47], v[160:163], v[198:201], v[44:47]
	v_mfma_f32_16x16x32_bf16 v[40:43], v[174:177], v[198:201], v[40:43]
	v_mfma_f32_16x16x32_bf16 v[36:39], v[160:163], v[220:223], v[36:39]
	v_mfma_f32_16x16x32_bf16 v[32:35], v[174:177], v[220:223], v[32:35]
	v_mfma_f32_16x16x32_bf16 v[68:71], v[170:173], v[186:189], v[68:71]
	v_mfma_f32_16x16x32_bf16 v[64:67], v[178:181], v[186:189], v[64:67]
	v_mfma_f32_16x16x32_bf16 v[52:55], v[170:173], v[194:197], v[52:55]
	v_mfma_f32_16x16x32_bf16 v[48:51], v[178:181], v[194:197], v[48:51]
	v_mfma_f32_16x16x32_bf16 v[44:47], v[170:173], v[216:219], v[44:47]
	v_mfma_f32_16x16x32_bf16 v[40:43], v[178:181], v[216:219], v[40:43]
	v_mfma_f32_16x16x32_bf16 v[36:39], v[170:173], v[224:227], v[36:39]
	v_mfma_f32_16x16x32_bf16 v[32:35], v[178:181], v[224:227], v[32:35]
	s_setprio 0
	s_barrier
; #define PG8_STAGE(bufoff, gbase, voff) do { _Pragma("unroll") for (int _i = 0; _i < 2; ++_i) \
;         __builtin_amdgcn_global_load_lds((const unsigned*)((const char*)(gbase) + (voff)[_i]), (LAS unsigned*)(lds + (bufoff) + ldsw + _i * 8192), 16, 0, 0); } while (0)
; #define PG8_LDA(dst, b, h) do { _Pragma("unroll") for (int m = 0; m < 4; ++m) _Pragma("unroll") for (int k = 0; k < 2; ++k) dst[m][k] = *(const LAS bf16x8*)(lds + PG8_SA(b, h) + aoff + m * 2048 + k * 1024); } while (0)
; #define PG8_MMA(ai, bj, At, Bt) do { __builtin_amdgcn_s_setprio(1); _Pragma("unroll") for (int m = 0; m < 4; ++m) _Pragma("unroll") for (int n = 0; n < 2; ++n) _Pragma("unroll") for (int k = 0; k < 2; ++k) \
;         acc[ai][bj][m][n] = __builtin_amdgcn_mfma_f32_16x16x32_bf16(Bt[n][k], At[m][k], acc[ai][bj][m][n], 0, 0, 0); __builtin_amdgcn_s_setprio(0); } while (0)
; #define PG8_WAIT_V(n) asm volatile("s_waitcnt vmcnt(" #n ")" ::: "memory")
; #define PG8_WAIT_L(n) asm volatile("s_waitcnt lgkmcnt(" #n ")" ::: "memory")
; #define PG8_BAR __builtin_amdgcn_s_barrier()
; #define PG8_SCHED __builtin_amdgcn_sched_barrier(0)
; template <class Epi, class Sched, bool ALIGN_EPI>
; __device__ __forceinline__ void gemm_phase(LAS unsigned char* lds, const Gemm g, const Sched& S, const Epi& E, const int tid) {
;     ...
;             PG8_LDA(At, 1, 1); PG8_STAGE(PG8_SB(1, 0), b3, voffB); PG8_STAGE(PG8_SB(1, 1), b3 + hstepB, voffB); PG8_STAGE(PG8_SA(1, 0), a3, voffA);
;             PG8_WAIT_V(8); PG8_WAIT_L(0); PG8_BAR; PG8_MMA(1, 0, At, B0); PG8_MMA(1, 1, At, B1); PG8_BAR; PG8_SCHED;
;         }
;         if constexpr (ALIGN_EPI) { if (wr == 0) PG8_BAR; }
	s_add_i32 s24, s53, s29
	v_lshl_add_u64 v[202:203], v[202:203], 0, s[2:3]
	s_mov_b32 m0, s24
	ds_read_b128 v[182:185], v142 offset:49152
	ds_read_b128 v[186:189], v142 offset:50176
	ds_read_b128 v[190:193], v142 offset:51200
	ds_read_b128 v[194:197], v142 offset:52224
	ds_read_b128 v[198:201], v142 offset:53248
	ds_read_b128 v[216:219], v142 offset:54272
	ds_read_b128 v[220:223], v142 offset:55296
	ds_read_b128 v[224:227], v142 offset:56320
	global_load_lds_dwordx4 v[202:203], off
	v_lshl_add_u64 v[202:203], v[204:205], 0, s[2:3]
	s_add_i32 m0, s24, 0x2000
	s_add_i32 s24, s54, s29
	global_load_lds_dwordx4 v[202:203], off
	v_lshl_add_u64 v[202:203], v[210:211], 0, s[2:3]
	s_mov_b32 m0, s24
	s_nop 0
	global_load_lds_dwordx4 v[202:203], off
	v_lshl_add_u64 v[202:203], v[212:213], 0, s[2:3]
	s_add_i32 m0, s24, 0x2000
	s_nop 0
	global_load_lds_dwordx4 v[202:203], off
	v_lshl_add_u64 v[202:203], v[228:229], 0, s[2:3]
	s_mov_b32 m0, s39
	s_nop 0
	global_load_lds_dwordx4 v[202:203], off
	v_lshl_add_u64 v[202:203], v[230:231], 0, s[2:3]
	s_mov_b32 m0, s40
	s_nop 0
	global_load_lds_dwordx4 v[202:203], off
	s_waitcnt vmcnt(8)
	s_waitcnt lgkmcnt(0)
	s_barrier
	s_setprio 1
	v_mfma_f32_16x16x32_bf16 v[92:95], v[144:147], v[182:185], v[92:95]
	v_mfma_f32_16x16x32_bf16 v[88:91], v[152:155], v[182:185], v[88:91]
	v_mfma_f32_16x16x32_bf16 v[84:87], v[144:147], v[190:193], v[84:87]
	v_mfma_f32_16x16x32_bf16 v[80:83], v[152:155], v[190:193], v[80:83]
	v_mfma_f32_16x16x32_bf16 v[76:79], v[144:147], v[198:201], v[76:79]
	v_mfma_f32_16x16x32_bf16 v[72:75], v[152:155], v[198:201], v[72:75]
	v_mfma_f32_16x16x32_bf16 v[60:63], v[144:147], v[220:223], v[60:63]
	v_mfma_f32_16x16x32_bf16 v[56:59], v[152:155], v[220:223], v[56:59]
	v_mfma_f32_16x16x32_bf16 v[92:95], v[148:151], v[186:189], v[92:95]
	v_mfma_f32_16x16x32_bf16 v[88:91], v[156:159], v[186:189], v[88:91]
	v_mfma_f32_16x16x32_bf16 v[84:87], v[148:151], v[194:197], v[84:87]
	v_mfma_f32_16x16x32_bf16 v[80:83], v[156:159], v[194:197], v[80:83]
	v_mfma_f32_16x16x32_bf16 v[76:79], v[148:151], v[216:219], v[76:79]
	v_mfma_f32_16x16x32_bf16 v[72:75], v[156:159], v[216:219], v[72:75]
	v_mfma_f32_16x16x32_bf16 v[60:63], v[148:151], v[224:227], v[60:63]
	v_mfma_f32_16x16x32_bf16 v[56:59], v[156:159], v[224:227], v[56:59]
	v_mfma_f32_16x16x32_bf16 v[28:31], v[160:163], v[182:185], v[28:31]
	v_mfma_f32_16x16x32_bf16 v[24:27], v[174:177], v[182:185], v[24:27]
	v_mfma_f32_16x16x32_bf16 v[20:23], v[160:163], v[190:193], v[20:23]
	v_mfma_f32_16x16x32_bf16 v[16:19], v[174:177], v[190:193], v[16:19]
	v_mfma_f32_16x16x32_bf16 v[12:15], v[160:163], v[198:201], v[12:15]
	v_mfma_f32_16x16x32_bf16 v[8:11], v[174:177], v[198:201], v[8:11]
	v_mfma_f32_16x16x32_bf16 v[4:7], v[160:163], v[220:223], v[4:7]
	v_mfma_f32_16x16x32_bf16 v[0:3], v[174:177], v[220:223], v[0:3]
	v_mfma_f32_16x16x32_bf16 v[28:31], v[170:173], v[186:189], v[28:31]
	v_mfma_f32_16x16x32_bf16 v[24:27], v[178:181], v[186:189], v[24:27]
	v_mfma_f32_16x16x32_bf16 v[20:23], v[170:173], v[194:197], v[20:23]
	v_mfma_f32_16x16x32_bf16 v[16:19], v[178:181], v[194:197], v[16:19]
	v_mfma_f32_16x16x32_bf16 v[12:15], v[170:173], v[216:219], v[12:15]
	v_mfma_f32_16x16x32_bf16 v[8:11], v[178:181], v[216:219], v[8:11]
	v_mfma_f32_16x16x32_bf16 v[4:7], v[170:173], v[224:227], v[4:7]
	v_mfma_f32_16x16x32_bf16 v[0:3], v[178:181], v[224:227], v[0:3]
	s_setprio 0
	s_barrier
	s_add_u32 s22, s22, 0x100
	s_addc_u32 s23, s23, 0
	s_add_u32 s50, s50, 0x100
	s_addc_u32 s51, s51, 0
	s_cmp_ge_u32 s52, s41
	s_mov_b32 s24, s52
	s_cbranch_scc0 .LBB0_615
	s_and_b64 vcc, exec, s[18:19]
	s_cbranch_vccz .LBB0_618
	s_barrier
